# phase0 mod_partials: row loads via SGPR base + SALU increments (fewer VALU slots)
# speedup vs baseline: 1.0112x; 1.0033x over previous
.LBB0_21:
	v_readfirstlane_b32 s98, v12
	v_readfirstlane_b32 s99, v13
	v_and_b32_e32 v27, 63, v18
	v_lshlrev_b32_e32 v27, 2, v27
	s_nop 3
	global_load_dword v132, v27, s[98:99] nt
	s_add_u32 s98, s98, 0x3000
	s_addc_u32 s99, s99, 0
	global_load_dword v133, v27, s[98:99] nt
	s_add_u32 s98, s98, 0x3000
	s_addc_u32 s99, s99, 0
	global_load_dword v134, v27, s[98:99] nt
	s_add_u32 s98, s98, 0x3000
	s_addc_u32 s99, s99, 0
	global_load_dword v135, v27, s[98:99] nt
	s_add_u32 s98, s98, 0x3000
	s_addc_u32 s99, s99, 0
	global_load_dword v136, v27, s[98:99] nt
	s_add_u32 s98, s98, 0x3000
	s_addc_u32 s99, s99, 0
	global_load_dword v137, v27, s[98:99] nt
	s_add_u32 s98, s98, 0x3000
	s_addc_u32 s99, s99, 0
	global_load_dword v138, v27, s[98:99] nt
	s_add_u32 s98, s98, 0x3000
	s_addc_u32 s99, s99, 0
	global_load_dword v139, v27, s[98:99] nt
	s_add_u32 s98, s98, 0x3000
	s_addc_u32 s99, s99, 0
	global_load_dword v140, v27, s[98:99] nt
	s_add_u32 s98, s98, 0x3000
	s_addc_u32 s99, s99, 0
	global_load_dword v141, v27, s[98:99] nt
	s_add_u32 s98, s98, 0x3000
	s_addc_u32 s99, s99, 0
	global_load_dword v142, v27, s[98:99] nt
	s_add_u32 s98, s98, 0x3000
	s_addc_u32 s99, s99, 0
	global_load_dword v143, v27, s[98:99] nt
	s_add_u32 s98, s98, 0x3000
	s_addc_u32 s99, s99, 0
	global_load_dword v144, v27, s[98:99] nt
	s_add_u32 s98, s98, 0x3000
	s_addc_u32 s99, s99, 0
	global_load_dword v145, v27, s[98:99] nt
	s_add_u32 s98, s98, 0x3000
	s_addc_u32 s99, s99, 0
	global_load_dword v146, v27, s[98:99] nt
	s_add_u32 s98, s98, 0x3000
	s_addc_u32 s99, s99, 0
	global_load_dword v147, v27, s[98:99] nt
	s_add_u32 s98, s98, 0x3000
	s_addc_u32 s99, s99, 0
	global_load_dword v148, v27, s[98:99] nt
	s_add_u32 s98, s98, 0x3000
	s_addc_u32 s99, s99, 0
	global_load_dword v149, v27, s[98:99] nt
	s_add_u32 s98, s98, 0x3000
	s_addc_u32 s99, s99, 0
	global_load_dword v150, v27, s[98:99] nt
	s_add_u32 s98, s98, 0x3000
	s_addc_u32 s99, s99, 0
	global_load_dword v151, v27, s[98:99] nt
	s_add_u32 s98, s98, 0x3000
	s_addc_u32 s99, s99, 0
	global_load_dword v152, v27, s[98:99] nt
	s_add_u32 s98, s98, 0x3000
	s_addc_u32 s99, s99, 0
	global_load_dword v153, v27, s[98:99] nt
	s_add_u32 s98, s98, 0x3000
	s_addc_u32 s99, s99, 0
	global_load_dword v154, v27, s[98:99] nt
	s_add_u32 s98, s98, 0x3000
	s_addc_u32 s99, s99, 0
	global_load_dword v155, v27, s[98:99] nt
	s_add_u32 s98, s98, 0x3000
	s_addc_u32 s99, s99, 0
	global_load_dword v156, v27, s[98:99] nt
	s_add_u32 s98, s98, 0x3000
	s_addc_u32 s99, s99, 0
	global_load_dword v157, v27, s[98:99] nt
	s_add_u32 s98, s98, 0x3000
	s_addc_u32 s99, s99, 0
	global_load_dword v158, v27, s[98:99] nt
	s_add_u32 s98, s98, 0x3000
	s_addc_u32 s99, s99, 0
	global_load_dword v159, v27, s[98:99] nt
	s_add_u32 s98, s98, 0x3000
	s_addc_u32 s99, s99, 0
	global_load_dword v160, v27, s[98:99] nt
	s_add_u32 s98, s98, 0x3000
	s_addc_u32 s99, s99, 0
	global_load_dword v161, v27, s[98:99] nt
	s_add_u32 s98, s98, 0x3000
	s_addc_u32 s99, s99, 0
	global_load_dword v162, v27, s[98:99] nt
	s_add_u32 s98, s98, 0x3000
	s_addc_u32 s99, s99, 0
	global_load_dword v163, v27, s[98:99] nt
	s_add_u32 s98, s98, 0x3000
	s_addc_u32 s99, s99, 0
	global_load_dword v164, v27, s[98:99] nt
	s_add_u32 s98, s98, 0x3000
	s_addc_u32 s99, s99, 0
	global_load_dword v165, v27, s[98:99] nt
	s_add_u32 s98, s98, 0x3000
	s_addc_u32 s99, s99, 0
	global_load_dword v166, v27, s[98:99] nt
	s_add_u32 s98, s98, 0x3000
	s_addc_u32 s99, s99, 0
	global_load_dword v167, v27, s[98:99] nt
	s_add_u32 s98, s98, 0x3000
	s_addc_u32 s99, s99, 0
	global_load_dword v168, v27, s[98:99] nt
	s_add_u32 s98, s98, 0x3000
	s_addc_u32 s99, s99, 0
	global_load_dword v169, v27, s[98:99] nt
	s_add_u32 s98, s98, 0x3000
	s_addc_u32 s99, s99, 0
	global_load_dword v170, v27, s[98:99] nt
	s_add_u32 s98, s98, 0x3000
	s_addc_u32 s99, s99, 0
	global_load_dword v171, v27, s[98:99] nt
	s_add_u32 s98, s98, 0x3000
	s_addc_u32 s99, s99, 0
	global_load_dword v172, v27, s[98:99] nt
	s_add_u32 s98, s98, 0x3000
	s_addc_u32 s99, s99, 0
	global_load_dword v173, v27, s[98:99] nt
	s_add_u32 s98, s98, 0x3000
	s_addc_u32 s99, s99, 0
	global_load_dword v174, v27, s[98:99] nt
	s_add_u32 s98, s98, 0x3000
	s_addc_u32 s99, s99, 0
	global_load_dword v175, v27, s[98:99] nt
	s_add_u32 s98, s98, 0x3000
	s_addc_u32 s99, s99, 0
	global_load_dword v176, v27, s[98:99] nt
	s_add_u32 s98, s98, 0x3000
	s_addc_u32 s99, s99, 0
	global_load_dword v177, v27, s[98:99] nt
	s_add_u32 s98, s98, 0x3000
	s_addc_u32 s99, s99, 0
	global_load_dword v178, v27, s[98:99] nt
	s_add_u32 s98, s98, 0x3000
	s_addc_u32 s99, s99, 0
	global_load_dword v179, v27, s[98:99] nt
	s_add_u32 s98, s98, 0x3000
	s_addc_u32 s99, s99, 0
	global_load_dword v180, v27, s[98:99] nt
	s_add_u32 s98, s98, 0x3000
	s_addc_u32 s99, s99, 0
	global_load_dword v181, v27, s[98:99] nt
	s_add_u32 s98, s98, 0x3000
	s_addc_u32 s99, s99, 0
	global_load_dword v182, v27, s[98:99] nt
	s_add_u32 s98, s98, 0x3000
	s_addc_u32 s99, s99, 0
	global_load_dword v183, v27, s[98:99] nt
	s_add_u32 s98, s98, 0x3000
	s_addc_u32 s99, s99, 0
	global_load_dword v184, v27, s[98:99] nt
	s_add_u32 s98, s98, 0x3000
	s_addc_u32 s99, s99, 0
	global_load_dword v185, v27, s[98:99] nt
	s_add_u32 s98, s98, 0x3000
	s_addc_u32 s99, s99, 0
	global_load_dword v186, v27, s[98:99] nt
	s_add_u32 s98, s98, 0x3000
	s_addc_u32 s99, s99, 0
	global_load_dword v187, v27, s[98:99] nt
	s_add_u32 s98, s98, 0x3000
	s_addc_u32 s99, s99, 0
	global_load_dword v188, v27, s[98:99] nt
	s_add_u32 s98, s98, 0x3000
	s_addc_u32 s99, s99, 0
	global_load_dword v189, v27, s[98:99] nt
	s_add_u32 s98, s98, 0x3000
	s_addc_u32 s99, s99, 0
	global_load_dword v190, v27, s[98:99] nt
	s_add_u32 s98, s98, 0x3000
	s_addc_u32 s99, s99, 0
	global_load_dword v191, v27, s[98:99] nt
	s_add_u32 s98, s98, 0x3000
	s_addc_u32 s99, s99, 0
	global_load_dword v192, v27, s[98:99] nt
	s_add_u32 s98, s98, 0x3000
	s_addc_u32 s99, s99, 0
	global_load_dword v193, v27, s[98:99] nt
	s_add_u32 s98, s98, 0x3000
	s_addc_u32 s99, s99, 0
	global_load_dword v194, v27, s[98:99] nt
	s_add_u32 s98, s98, 0x3000
	s_addc_u32 s99, s99, 0
	global_load_dword v195, v27, s[98:99] nt
	v_readlane_b32 s12, v0, 0
	v_readlane_b32 s13, v23, 0
	v_readlane_b32 s14, v24, 0
	v_readlane_b32 s15, v25, 0
	v_readlane_b32 s16, v26, 0
	s_waitcnt vmcnt(63)
	v_pk_fma_f32 v[10:11], v[132:133], s[12:13], v[10:11] op_sel_hi:[0,1,1]
	v_pk_fma_f32 v[8:9], v[132:133], s[14:15], v[8:9] op_sel_hi:[0,1,1]
	v_fmac_f32_e32 v22, s16, v132
	v_readlane_b32 s12, v0, 1
	v_readlane_b32 s13, v23, 1
	v_readlane_b32 s14, v24, 1
	v_readlane_b32 s15, v25, 1
	v_readlane_b32 s16, v26, 1
	s_waitcnt vmcnt(62)
	v_pk_fma_f32 v[10:11], v[132:133], s[12:13], v[10:11] op_sel:[1,0,0] op_sel_hi:[1,1,1]
	v_pk_fma_f32 v[8:9], v[132:133], s[14:15], v[8:9] op_sel:[1,0,0] op_sel_hi:[1,1,1]
	v_fmac_f32_e32 v22, s16, v133
	v_readlane_b32 s12, v0, 2
	v_readlane_b32 s13, v23, 2
	v_readlane_b32 s14, v24, 2
	v_readlane_b32 s15, v25, 2
	v_readlane_b32 s16, v26, 2
	s_waitcnt vmcnt(61)
	v_pk_fma_f32 v[10:11], v[134:135], s[12:13], v[10:11] op_sel_hi:[0,1,1]
	v_pk_fma_f32 v[8:9], v[134:135], s[14:15], v[8:9] op_sel_hi:[0,1,1]
	v_fmac_f32_e32 v22, s16, v134
	v_readlane_b32 s12, v0, 3
	v_readlane_b32 s13, v23, 3
	v_readlane_b32 s14, v24, 3
	v_readlane_b32 s15, v25, 3
	v_readlane_b32 s16, v26, 3
	s_waitcnt vmcnt(60)
	v_pk_fma_f32 v[10:11], v[134:135], s[12:13], v[10:11] op_sel:[1,0,0] op_sel_hi:[1,1,1]
	v_pk_fma_f32 v[8:9], v[134:135], s[14:15], v[8:9] op_sel:[1,0,0] op_sel_hi:[1,1,1]
	v_fmac_f32_e32 v22, s16, v135
	v_readlane_b32 s12, v0, 4
	v_readlane_b32 s13, v23, 4
	v_readlane_b32 s14, v24, 4
	v_readlane_b32 s15, v25, 4
	v_readlane_b32 s16, v26, 4
	s_waitcnt vmcnt(59)
	v_pk_fma_f32 v[10:11], v[136:137], s[12:13], v[10:11] op_sel_hi:[0,1,1]
	v_pk_fma_f32 v[8:9], v[136:137], s[14:15], v[8:9] op_sel_hi:[0,1,1]
	v_fmac_f32_e32 v22, s16, v136
	v_readlane_b32 s12, v0, 5
	v_readlane_b32 s13, v23, 5
	v_readlane_b32 s14, v24, 5
	v_readlane_b32 s15, v25, 5
	v_readlane_b32 s16, v26, 5
	s_waitcnt vmcnt(58)
	v_pk_fma_f32 v[10:11], v[136:137], s[12:13], v[10:11] op_sel:[1,0,0] op_sel_hi:[1,1,1]
	v_pk_fma_f32 v[8:9], v[136:137], s[14:15], v[8:9] op_sel:[1,0,0] op_sel_hi:[1,1,1]
	v_fmac_f32_e32 v22, s16, v137
	v_readlane_b32 s12, v0, 6
	v_readlane_b32 s13, v23, 6
	v_readlane_b32 s14, v24, 6
	v_readlane_b32 s15, v25, 6
	v_readlane_b32 s16, v26, 6
	s_waitcnt vmcnt(57)
	v_pk_fma_f32 v[10:11], v[138:139], s[12:13], v[10:11] op_sel_hi:[0,1,1]
	v_pk_fma_f32 v[8:9], v[138:139], s[14:15], v[8:9] op_sel_hi:[0,1,1]
	v_fmac_f32_e32 v22, s16, v138
	v_readlane_b32 s12, v0, 7
	v_readlane_b32 s13, v23, 7
	v_readlane_b32 s14, v24, 7
	v_readlane_b32 s15, v25, 7
	v_readlane_b32 s16, v26, 7
	s_waitcnt vmcnt(56)
	v_pk_fma_f32 v[10:11], v[138:139], s[12:13], v[10:11] op_sel:[1,0,0] op_sel_hi:[1,1,1]
	v_pk_fma_f32 v[8:9], v[138:139], s[14:15], v[8:9] op_sel:[1,0,0] op_sel_hi:[1,1,1]
	v_fmac_f32_e32 v22, s16, v139
	v_readlane_b32 s12, v0, 8
	v_readlane_b32 s13, v23, 8
	v_readlane_b32 s14, v24, 8
	v_readlane_b32 s15, v25, 8
	v_readlane_b32 s16, v26, 8
	s_waitcnt vmcnt(55)
	v_pk_fma_f32 v[10:11], v[140:141], s[12:13], v[10:11] op_sel_hi:[0,1,1]
	v_pk_fma_f32 v[8:9], v[140:141], s[14:15], v[8:9] op_sel_hi:[0,1,1]
	v_fmac_f32_e32 v22, s16, v140
	v_readlane_b32 s12, v0, 9
	v_readlane_b32 s13, v23, 9
	v_readlane_b32 s14, v24, 9
	v_readlane_b32 s15, v25, 9
	v_readlane_b32 s16, v26, 9
	s_waitcnt vmcnt(54)
	v_pk_fma_f32 v[10:11], v[140:141], s[12:13], v[10:11] op_sel:[1,0,0] op_sel_hi:[1,1,1]
	v_pk_fma_f32 v[8:9], v[140:141], s[14:15], v[8:9] op_sel:[1,0,0] op_sel_hi:[1,1,1]
	v_fmac_f32_e32 v22, s16, v141
	v_readlane_b32 s12, v0, 10
	v_readlane_b32 s13, v23, 10
	v_readlane_b32 s14, v24, 10
	v_readlane_b32 s15, v25, 10
	v_readlane_b32 s16, v26, 10
	s_waitcnt vmcnt(53)
	v_pk_fma_f32 v[10:11], v[142:143], s[12:13], v[10:11] op_sel_hi:[0,1,1]
	v_pk_fma_f32 v[8:9], v[142:143], s[14:15], v[8:9] op_sel_hi:[0,1,1]
	v_fmac_f32_e32 v22, s16, v142
	v_readlane_b32 s12, v0, 11
	v_readlane_b32 s13, v23, 11
	v_readlane_b32 s14, v24, 11
	v_readlane_b32 s15, v25, 11
	v_readlane_b32 s16, v26, 11
	s_waitcnt vmcnt(52)
	v_pk_fma_f32 v[10:11], v[142:143], s[12:13], v[10:11] op_sel:[1,0,0] op_sel_hi:[1,1,1]
	v_pk_fma_f32 v[8:9], v[142:143], s[14:15], v[8:9] op_sel:[1,0,0] op_sel_hi:[1,1,1]
	v_fmac_f32_e32 v22, s16, v143
	v_readlane_b32 s12, v0, 12
	v_readlane_b32 s13, v23, 12
	v_readlane_b32 s14, v24, 12
	v_readlane_b32 s15, v25, 12
	v_readlane_b32 s16, v26, 12
	s_waitcnt vmcnt(51)
	v_pk_fma_f32 v[10:11], v[144:145], s[12:13], v[10:11] op_sel_hi:[0,1,1]
	v_pk_fma_f32 v[8:9], v[144:145], s[14:15], v[8:9] op_sel_hi:[0,1,1]
	v_fmac_f32_e32 v22, s16, v144
	v_readlane_b32 s12, v0, 13
	v_readlane_b32 s13, v23, 13
	v_readlane_b32 s14, v24, 13
	v_readlane_b32 s15, v25, 13
	v_readlane_b32 s16, v26, 13
	s_waitcnt vmcnt(50)
	v_pk_fma_f32 v[10:11], v[144:145], s[12:13], v[10:11] op_sel:[1,0,0] op_sel_hi:[1,1,1]
	v_pk_fma_f32 v[8:9], v[144:145], s[14:15], v[8:9] op_sel:[1,0,0] op_sel_hi:[1,1,1]
	v_fmac_f32_e32 v22, s16, v145
	v_readlane_b32 s12, v0, 14
	v_readlane_b32 s13, v23, 14
	v_readlane_b32 s14, v24, 14
	v_readlane_b32 s15, v25, 14
	v_readlane_b32 s16, v26, 14
	s_waitcnt vmcnt(49)
	v_pk_fma_f32 v[10:11], v[146:147], s[12:13], v[10:11] op_sel_hi:[0,1,1]
	v_pk_fma_f32 v[8:9], v[146:147], s[14:15], v[8:9] op_sel_hi:[0,1,1]
	v_fmac_f32_e32 v22, s16, v146
	v_readlane_b32 s12, v0, 15
	v_readlane_b32 s13, v23, 15
	v_readlane_b32 s14, v24, 15
	v_readlane_b32 s15, v25, 15
	v_readlane_b32 s16, v26, 15
	s_waitcnt vmcnt(48)
	v_pk_fma_f32 v[10:11], v[146:147], s[12:13], v[10:11] op_sel:[1,0,0] op_sel_hi:[1,1,1]
	v_pk_fma_f32 v[8:9], v[146:147], s[14:15], v[8:9] op_sel:[1,0,0] op_sel_hi:[1,1,1]
	v_fmac_f32_e32 v22, s16, v147
	v_readlane_b32 s12, v0, 16
	v_readlane_b32 s13, v23, 16
	v_readlane_b32 s14, v24, 16
	v_readlane_b32 s15, v25, 16
	v_readlane_b32 s16, v26, 16
	s_waitcnt vmcnt(47)
	v_pk_fma_f32 v[10:11], v[148:149], s[12:13], v[10:11] op_sel_hi:[0,1,1]
	v_pk_fma_f32 v[8:9], v[148:149], s[14:15], v[8:9] op_sel_hi:[0,1,1]
	v_fmac_f32_e32 v22, s16, v148
	v_readlane_b32 s12, v0, 17
	v_readlane_b32 s13, v23, 17
	v_readlane_b32 s14, v24, 17
	v_readlane_b32 s15, v25, 17
	v_readlane_b32 s16, v26, 17
	s_waitcnt vmcnt(46)
	v_pk_fma_f32 v[10:11], v[148:149], s[12:13], v[10:11] op_sel:[1,0,0] op_sel_hi:[1,1,1]
	v_pk_fma_f32 v[8:9], v[148:149], s[14:15], v[8:9] op_sel:[1,0,0] op_sel_hi:[1,1,1]
	v_fmac_f32_e32 v22, s16, v149
	v_readlane_b32 s12, v0, 18
	v_readlane_b32 s13, v23, 18
	v_readlane_b32 s14, v24, 18
	v_readlane_b32 s15, v25, 18
	v_readlane_b32 s16, v26, 18
	s_waitcnt vmcnt(45)
	v_pk_fma_f32 v[10:11], v[150:151], s[12:13], v[10:11] op_sel_hi:[0,1,1]
	v_pk_fma_f32 v[8:9], v[150:151], s[14:15], v[8:9] op_sel_hi:[0,1,1]
	v_fmac_f32_e32 v22, s16, v150
	v_readlane_b32 s12, v0, 19
	v_readlane_b32 s13, v23, 19
	v_readlane_b32 s14, v24, 19
	v_readlane_b32 s15, v25, 19
	v_readlane_b32 s16, v26, 19
	s_waitcnt vmcnt(44)
	v_pk_fma_f32 v[10:11], v[150:151], s[12:13], v[10:11] op_sel:[1,0,0] op_sel_hi:[1,1,1]
	v_pk_fma_f32 v[8:9], v[150:151], s[14:15], v[8:9] op_sel:[1,0,0] op_sel_hi:[1,1,1]
	v_fmac_f32_e32 v22, s16, v151
	v_readlane_b32 s12, v0, 20
	v_readlane_b32 s13, v23, 20
	v_readlane_b32 s14, v24, 20
	v_readlane_b32 s15, v25, 20
	v_readlane_b32 s16, v26, 20
	s_waitcnt vmcnt(43)
	v_pk_fma_f32 v[10:11], v[152:153], s[12:13], v[10:11] op_sel_hi:[0,1,1]
	v_pk_fma_f32 v[8:9], v[152:153], s[14:15], v[8:9] op_sel_hi:[0,1,1]
	v_fmac_f32_e32 v22, s16, v152
	v_readlane_b32 s12, v0, 21
	v_readlane_b32 s13, v23, 21
	v_readlane_b32 s14, v24, 21
	v_readlane_b32 s15, v25, 21
	v_readlane_b32 s16, v26, 21
	s_waitcnt vmcnt(42)
	v_pk_fma_f32 v[10:11], v[152:153], s[12:13], v[10:11] op_sel:[1,0,0] op_sel_hi:[1,1,1]
	v_pk_fma_f32 v[8:9], v[152:153], s[14:15], v[8:9] op_sel:[1,0,0] op_sel_hi:[1,1,1]
	v_fmac_f32_e32 v22, s16, v153
	v_readlane_b32 s12, v0, 22
	v_readlane_b32 s13, v23, 22
	v_readlane_b32 s14, v24, 22
	v_readlane_b32 s15, v25, 22
	v_readlane_b32 s16, v26, 22
	s_waitcnt vmcnt(41)
	v_pk_fma_f32 v[10:11], v[154:155], s[12:13], v[10:11] op_sel_hi:[0,1,1]
	v_pk_fma_f32 v[8:9], v[154:155], s[14:15], v[8:9] op_sel_hi:[0,1,1]
	v_fmac_f32_e32 v22, s16, v154
	v_readlane_b32 s12, v0, 23
	v_readlane_b32 s13, v23, 23
	v_readlane_b32 s14, v24, 23
	v_readlane_b32 s15, v25, 23
	v_readlane_b32 s16, v26, 23
	s_waitcnt vmcnt(40)
	v_pk_fma_f32 v[10:11], v[154:155], s[12:13], v[10:11] op_sel:[1,0,0] op_sel_hi:[1,1,1]
	v_pk_fma_f32 v[8:9], v[154:155], s[14:15], v[8:9] op_sel:[1,0,0] op_sel_hi:[1,1,1]
	v_fmac_f32_e32 v22, s16, v155
	v_readlane_b32 s12, v0, 24
	v_readlane_b32 s13, v23, 24
	v_readlane_b32 s14, v24, 24
	v_readlane_b32 s15, v25, 24
	v_readlane_b32 s16, v26, 24
	s_waitcnt vmcnt(39)
	v_pk_fma_f32 v[10:11], v[156:157], s[12:13], v[10:11] op_sel_hi:[0,1,1]
	v_pk_fma_f32 v[8:9], v[156:157], s[14:15], v[8:9] op_sel_hi:[0,1,1]
	v_fmac_f32_e32 v22, s16, v156
	v_readlane_b32 s12, v0, 25
	v_readlane_b32 s13, v23, 25
	v_readlane_b32 s14, v24, 25
	v_readlane_b32 s15, v25, 25
	v_readlane_b32 s16, v26, 25
	s_waitcnt vmcnt(38)
	v_pk_fma_f32 v[10:11], v[156:157], s[12:13], v[10:11] op_sel:[1,0,0] op_sel_hi:[1,1,1]
	v_pk_fma_f32 v[8:9], v[156:157], s[14:15], v[8:9] op_sel:[1,0,0] op_sel_hi:[1,1,1]
	v_fmac_f32_e32 v22, s16, v157
	v_readlane_b32 s12, v0, 26
	v_readlane_b32 s13, v23, 26
	v_readlane_b32 s14, v24, 26
	v_readlane_b32 s15, v25, 26
	v_readlane_b32 s16, v26, 26
	s_waitcnt vmcnt(37)
	v_pk_fma_f32 v[10:11], v[158:159], s[12:13], v[10:11] op_sel_hi:[0,1,1]
	v_pk_fma_f32 v[8:9], v[158:159], s[14:15], v[8:9] op_sel_hi:[0,1,1]
	v_fmac_f32_e32 v22, s16, v158
	v_readlane_b32 s12, v0, 27
	v_readlane_b32 s13, v23, 27
	v_readlane_b32 s14, v24, 27
	v_readlane_b32 s15, v25, 27
	v_readlane_b32 s16, v26, 27
	s_waitcnt vmcnt(36)
	v_pk_fma_f32 v[10:11], v[158:159], s[12:13], v[10:11] op_sel:[1,0,0] op_sel_hi:[1,1,1]
	v_pk_fma_f32 v[8:9], v[158:159], s[14:15], v[8:9] op_sel:[1,0,0] op_sel_hi:[1,1,1]
	v_fmac_f32_e32 v22, s16, v159
	v_readlane_b32 s12, v0, 28
	v_readlane_b32 s13, v23, 28
	v_readlane_b32 s14, v24, 28
	v_readlane_b32 s15, v25, 28
	v_readlane_b32 s16, v26, 28
	s_waitcnt vmcnt(35)
	v_pk_fma_f32 v[10:11], v[160:161], s[12:13], v[10:11] op_sel_hi:[0,1,1]
	v_pk_fma_f32 v[8:9], v[160:161], s[14:15], v[8:9] op_sel_hi:[0,1,1]
	v_fmac_f32_e32 v22, s16, v160
	v_readlane_b32 s12, v0, 29
	v_readlane_b32 s13, v23, 29
	v_readlane_b32 s14, v24, 29
	v_readlane_b32 s15, v25, 29
	v_readlane_b32 s16, v26, 29
	s_waitcnt vmcnt(34)
	v_pk_fma_f32 v[10:11], v[160:161], s[12:13], v[10:11] op_sel:[1,0,0] op_sel_hi:[1,1,1]
	v_pk_fma_f32 v[8:9], v[160:161], s[14:15], v[8:9] op_sel:[1,0,0] op_sel_hi:[1,1,1]
	v_fmac_f32_e32 v22, s16, v161
	v_readlane_b32 s12, v0, 30
	v_readlane_b32 s13, v23, 30
	v_readlane_b32 s14, v24, 30
	v_readlane_b32 s15, v25, 30
	v_readlane_b32 s16, v26, 30
	s_waitcnt vmcnt(33)
	v_pk_fma_f32 v[10:11], v[162:163], s[12:13], v[10:11] op_sel_hi:[0,1,1]
	v_pk_fma_f32 v[8:9], v[162:163], s[14:15], v[8:9] op_sel_hi:[0,1,1]
	v_fmac_f32_e32 v22, s16, v162
	v_readlane_b32 s12, v0, 31
	v_readlane_b32 s13, v23, 31
	v_readlane_b32 s14, v24, 31
	v_readlane_b32 s15, v25, 31
	v_readlane_b32 s16, v26, 31
	s_waitcnt vmcnt(32)
	v_pk_fma_f32 v[10:11], v[162:163], s[12:13], v[10:11] op_sel:[1,0,0] op_sel_hi:[1,1,1]
	v_pk_fma_f32 v[8:9], v[162:163], s[14:15], v[8:9] op_sel:[1,0,0] op_sel_hi:[1,1,1]
	v_fmac_f32_e32 v22, s16, v163
	v_readlane_b32 s12, v0, 32
	v_readlane_b32 s13, v23, 32
	v_readlane_b32 s14, v24, 32
	v_readlane_b32 s15, v25, 32
	v_readlane_b32 s16, v26, 32
	s_waitcnt vmcnt(31)
	v_pk_fma_f32 v[10:11], v[164:165], s[12:13], v[10:11] op_sel_hi:[0,1,1]
	v_pk_fma_f32 v[8:9], v[164:165], s[14:15], v[8:9] op_sel_hi:[0,1,1]
	v_fmac_f32_e32 v22, s16, v164
	v_readlane_b32 s12, v0, 33
	v_readlane_b32 s13, v23, 33
	v_readlane_b32 s14, v24, 33
	v_readlane_b32 s15, v25, 33
	v_readlane_b32 s16, v26, 33
	s_waitcnt vmcnt(30)
	v_pk_fma_f32 v[10:11], v[164:165], s[12:13], v[10:11] op_sel:[1,0,0] op_sel_hi:[1,1,1]
	v_pk_fma_f32 v[8:9], v[164:165], s[14:15], v[8:9] op_sel:[1,0,0] op_sel_hi:[1,1,1]
	v_fmac_f32_e32 v22, s16, v165
	v_readlane_b32 s12, v0, 34
	v_readlane_b32 s13, v23, 34
	v_readlane_b32 s14, v24, 34
	v_readlane_b32 s15, v25, 34
	v_readlane_b32 s16, v26, 34
	s_waitcnt vmcnt(29)
	v_pk_fma_f32 v[10:11], v[166:167], s[12:13], v[10:11] op_sel_hi:[0,1,1]
	v_pk_fma_f32 v[8:9], v[166:167], s[14:15], v[8:9] op_sel_hi:[0,1,1]
	v_fmac_f32_e32 v22, s16, v166
	v_readlane_b32 s12, v0, 35
	v_readlane_b32 s13, v23, 35
	v_readlane_b32 s14, v24, 35
	v_readlane_b32 s15, v25, 35
	v_readlane_b32 s16, v26, 35
	s_waitcnt vmcnt(28)
	v_pk_fma_f32 v[10:11], v[166:167], s[12:13], v[10:11] op_sel:[1,0,0] op_sel_hi:[1,1,1]
	v_pk_fma_f32 v[8:9], v[166:167], s[14:15], v[8:9] op_sel:[1,0,0] op_sel_hi:[1,1,1]
	v_fmac_f32_e32 v22, s16, v167
	v_readlane_b32 s12, v0, 36
	v_readlane_b32 s13, v23, 36
	v_readlane_b32 s14, v24, 36
	v_readlane_b32 s15, v25, 36
	v_readlane_b32 s16, v26, 36
	s_waitcnt vmcnt(27)
	v_pk_fma_f32 v[10:11], v[168:169], s[12:13], v[10:11] op_sel_hi:[0,1,1]
	v_pk_fma_f32 v[8:9], v[168:169], s[14:15], v[8:9] op_sel_hi:[0,1,1]
	v_fmac_f32_e32 v22, s16, v168
	v_readlane_b32 s12, v0, 37
	v_readlane_b32 s13, v23, 37
	v_readlane_b32 s14, v24, 37
	v_readlane_b32 s15, v25, 37
	v_readlane_b32 s16, v26, 37
	s_waitcnt vmcnt(26)
	v_pk_fma_f32 v[10:11], v[168:169], s[12:13], v[10:11] op_sel:[1,0,0] op_sel_hi:[1,1,1]
	v_pk_fma_f32 v[8:9], v[168:169], s[14:15], v[8:9] op_sel:[1,0,0] op_sel_hi:[1,1,1]
	v_fmac_f32_e32 v22, s16, v169
	v_readlane_b32 s12, v0, 38
	v_readlane_b32 s13, v23, 38
	v_readlane_b32 s14, v24, 38
	v_readlane_b32 s15, v25, 38
	v_readlane_b32 s16, v26, 38
	s_waitcnt vmcnt(25)
	v_pk_fma_f32 v[10:11], v[170:171], s[12:13], v[10:11] op_sel_hi:[0,1,1]
	v_pk_fma_f32 v[8:9], v[170:171], s[14:15], v[8:9] op_sel_hi:[0,1,1]
	v_fmac_f32_e32 v22, s16, v170
	v_readlane_b32 s12, v0, 39
	v_readlane_b32 s13, v23, 39
	v_readlane_b32 s14, v24, 39
	v_readlane_b32 s15, v25, 39
	v_readlane_b32 s16, v26, 39
	s_waitcnt vmcnt(24)
	v_pk_fma_f32 v[10:11], v[170:171], s[12:13], v[10:11] op_sel:[1,0,0] op_sel_hi:[1,1,1]
	v_pk_fma_f32 v[8:9], v[170:171], s[14:15], v[8:9] op_sel:[1,0,0] op_sel_hi:[1,1,1]
	v_fmac_f32_e32 v22, s16, v171
	v_readlane_b32 s12, v0, 40
	v_readlane_b32 s13, v23, 40
	v_readlane_b32 s14, v24, 40
	v_readlane_b32 s15, v25, 40
	v_readlane_b32 s16, v26, 40
	s_waitcnt vmcnt(23)
	v_pk_fma_f32 v[10:11], v[172:173], s[12:13], v[10:11] op_sel_hi:[0,1,1]
	v_pk_fma_f32 v[8:9], v[172:173], s[14:15], v[8:9] op_sel_hi:[0,1,1]
	v_fmac_f32_e32 v22, s16, v172
	v_readlane_b32 s12, v0, 41
	v_readlane_b32 s13, v23, 41
	v_readlane_b32 s14, v24, 41
	v_readlane_b32 s15, v25, 41
	v_readlane_b32 s16, v26, 41
	s_waitcnt vmcnt(22)
	v_pk_fma_f32 v[10:11], v[172:173], s[12:13], v[10:11] op_sel:[1,0,0] op_sel_hi:[1,1,1]
	v_pk_fma_f32 v[8:9], v[172:173], s[14:15], v[8:9] op_sel:[1,0,0] op_sel_hi:[1,1,1]
	v_fmac_f32_e32 v22, s16, v173
	v_readlane_b32 s12, v0, 42
	v_readlane_b32 s13, v23, 42
	v_readlane_b32 s14, v24, 42
	v_readlane_b32 s15, v25, 42
	v_readlane_b32 s16, v26, 42
	s_waitcnt vmcnt(21)
	v_pk_fma_f32 v[10:11], v[174:175], s[12:13], v[10:11] op_sel_hi:[0,1,1]
	v_pk_fma_f32 v[8:9], v[174:175], s[14:15], v[8:9] op_sel_hi:[0,1,1]
	v_fmac_f32_e32 v22, s16, v174
	v_readlane_b32 s12, v0, 43
	v_readlane_b32 s13, v23, 43
	v_readlane_b32 s14, v24, 43
	v_readlane_b32 s15, v25, 43
	v_readlane_b32 s16, v26, 43
	s_waitcnt vmcnt(20)
	v_pk_fma_f32 v[10:11], v[174:175], s[12:13], v[10:11] op_sel:[1,0,0] op_sel_hi:[1,1,1]
	v_pk_fma_f32 v[8:9], v[174:175], s[14:15], v[8:9] op_sel:[1,0,0] op_sel_hi:[1,1,1]
	v_fmac_f32_e32 v22, s16, v175
	v_readlane_b32 s12, v0, 44
	v_readlane_b32 s13, v23, 44
	v_readlane_b32 s14, v24, 44
	v_readlane_b32 s15, v25, 44
	v_readlane_b32 s16, v26, 44
	s_waitcnt vmcnt(19)
	v_pk_fma_f32 v[10:11], v[176:177], s[12:13], v[10:11] op_sel_hi:[0,1,1]
	v_pk_fma_f32 v[8:9], v[176:177], s[14:15], v[8:9] op_sel_hi:[0,1,1]
	v_fmac_f32_e32 v22, s16, v176
	v_readlane_b32 s12, v0, 45
	v_readlane_b32 s13, v23, 45
	v_readlane_b32 s14, v24, 45
	v_readlane_b32 s15, v25, 45
	v_readlane_b32 s16, v26, 45
	s_waitcnt vmcnt(18)
	v_pk_fma_f32 v[10:11], v[176:177], s[12:13], v[10:11] op_sel:[1,0,0] op_sel_hi:[1,1,1]
	v_pk_fma_f32 v[8:9], v[176:177], s[14:15], v[8:9] op_sel:[1,0,0] op_sel_hi:[1,1,1]
	v_fmac_f32_e32 v22, s16, v177
	v_readlane_b32 s12, v0, 46
	v_readlane_b32 s13, v23, 46
	v_readlane_b32 s14, v24, 46
	v_readlane_b32 s15, v25, 46
	v_readlane_b32 s16, v26, 46
	s_waitcnt vmcnt(17)
	v_pk_fma_f32 v[10:11], v[178:179], s[12:13], v[10:11] op_sel_hi:[0,1,1]
	v_pk_fma_f32 v[8:9], v[178:179], s[14:15], v[8:9] op_sel_hi:[0,1,1]
	v_fmac_f32_e32 v22, s16, v178
	v_readlane_b32 s12, v0, 47
	v_readlane_b32 s13, v23, 47
	v_readlane_b32 s14, v24, 47
	v_readlane_b32 s15, v25, 47
	v_readlane_b32 s16, v26, 47
	s_waitcnt vmcnt(16)
	v_pk_fma_f32 v[10:11], v[178:179], s[12:13], v[10:11] op_sel:[1,0,0] op_sel_hi:[1,1,1]
	v_pk_fma_f32 v[8:9], v[178:179], s[14:15], v[8:9] op_sel:[1,0,0] op_sel_hi:[1,1,1]
	v_fmac_f32_e32 v22, s16, v179
	v_readlane_b32 s12, v0, 48
	v_readlane_b32 s13, v23, 48
	v_readlane_b32 s14, v24, 48
	v_readlane_b32 s15, v25, 48
	v_readlane_b32 s16, v26, 48
	s_waitcnt vmcnt(15)
	v_pk_fma_f32 v[10:11], v[180:181], s[12:13], v[10:11] op_sel_hi:[0,1,1]
	v_pk_fma_f32 v[8:9], v[180:181], s[14:15], v[8:9] op_sel_hi:[0,1,1]
	v_fmac_f32_e32 v22, s16, v180
	v_readlane_b32 s12, v0, 49
	v_readlane_b32 s13, v23, 49
	v_readlane_b32 s14, v24, 49
	v_readlane_b32 s15, v25, 49
	v_readlane_b32 s16, v26, 49
	s_waitcnt vmcnt(14)
	v_pk_fma_f32 v[10:11], v[180:181], s[12:13], v[10:11] op_sel:[1,0,0] op_sel_hi:[1,1,1]
	v_pk_fma_f32 v[8:9], v[180:181], s[14:15], v[8:9] op_sel:[1,0,0] op_sel_hi:[1,1,1]
	v_fmac_f32_e32 v22, s16, v181
	v_readlane_b32 s12, v0, 50
	v_readlane_b32 s13, v23, 50
	v_readlane_b32 s14, v24, 50
	v_readlane_b32 s15, v25, 50
	v_readlane_b32 s16, v26, 50
	s_waitcnt vmcnt(13)
	v_pk_fma_f32 v[10:11], v[182:183], s[12:13], v[10:11] op_sel_hi:[0,1,1]
	v_pk_fma_f32 v[8:9], v[182:183], s[14:15], v[8:9] op_sel_hi:[0,1,1]
	v_fmac_f32_e32 v22, s16, v182
	v_readlane_b32 s12, v0, 51
	v_readlane_b32 s13, v23, 51
	v_readlane_b32 s14, v24, 51
	v_readlane_b32 s15, v25, 51
	v_readlane_b32 s16, v26, 51
	s_waitcnt vmcnt(12)
	v_pk_fma_f32 v[10:11], v[182:183], s[12:13], v[10:11] op_sel:[1,0,0] op_sel_hi:[1,1,1]
	v_pk_fma_f32 v[8:9], v[182:183], s[14:15], v[8:9] op_sel:[1,0,0] op_sel_hi:[1,1,1]
	v_fmac_f32_e32 v22, s16, v183
	v_readlane_b32 s12, v0, 52
	v_readlane_b32 s13, v23, 52
	v_readlane_b32 s14, v24, 52
	v_readlane_b32 s15, v25, 52
	v_readlane_b32 s16, v26, 52
	s_waitcnt vmcnt(11)
	v_pk_fma_f32 v[10:11], v[184:185], s[12:13], v[10:11] op_sel_hi:[0,1,1]
	v_pk_fma_f32 v[8:9], v[184:185], s[14:15], v[8:9] op_sel_hi:[0,1,1]
	v_fmac_f32_e32 v22, s16, v184
	v_readlane_b32 s12, v0, 53
	v_readlane_b32 s13, v23, 53
	v_readlane_b32 s14, v24, 53
	v_readlane_b32 s15, v25, 53
	v_readlane_b32 s16, v26, 53
	s_waitcnt vmcnt(10)
	v_pk_fma_f32 v[10:11], v[184:185], s[12:13], v[10:11] op_sel:[1,0,0] op_sel_hi:[1,1,1]
	v_pk_fma_f32 v[8:9], v[184:185], s[14:15], v[8:9] op_sel:[1,0,0] op_sel_hi:[1,1,1]
	v_fmac_f32_e32 v22, s16, v185
	v_readlane_b32 s12, v0, 54
	v_readlane_b32 s13, v23, 54
	v_readlane_b32 s14, v24, 54
	v_readlane_b32 s15, v25, 54
	v_readlane_b32 s16, v26, 54
	s_waitcnt vmcnt(9)
	v_pk_fma_f32 v[10:11], v[186:187], s[12:13], v[10:11] op_sel_hi:[0,1,1]
	v_pk_fma_f32 v[8:9], v[186:187], s[14:15], v[8:9] op_sel_hi:[0,1,1]
	v_fmac_f32_e32 v22, s16, v186
	v_readlane_b32 s12, v0, 55
	v_readlane_b32 s13, v23, 55
	v_readlane_b32 s14, v24, 55
	v_readlane_b32 s15, v25, 55
	v_readlane_b32 s16, v26, 55
	s_waitcnt vmcnt(8)
	v_pk_fma_f32 v[10:11], v[186:187], s[12:13], v[10:11] op_sel:[1,0,0] op_sel_hi:[1,1,1]
	v_pk_fma_f32 v[8:9], v[186:187], s[14:15], v[8:9] op_sel:[1,0,0] op_sel_hi:[1,1,1]
	v_fmac_f32_e32 v22, s16, v187
	v_readlane_b32 s12, v0, 56
	v_readlane_b32 s13, v23, 56
	v_readlane_b32 s14, v24, 56
	v_readlane_b32 s15, v25, 56
	v_readlane_b32 s16, v26, 56
	s_waitcnt vmcnt(7)
	v_pk_fma_f32 v[10:11], v[188:189], s[12:13], v[10:11] op_sel_hi:[0,1,1]
	v_pk_fma_f32 v[8:9], v[188:189], s[14:15], v[8:9] op_sel_hi:[0,1,1]
	v_fmac_f32_e32 v22, s16, v188
	v_readlane_b32 s12, v0, 57
	v_readlane_b32 s13, v23, 57
	v_readlane_b32 s14, v24, 57
	v_readlane_b32 s15, v25, 57
	v_readlane_b32 s16, v26, 57
	s_waitcnt vmcnt(6)
	v_pk_fma_f32 v[10:11], v[188:189], s[12:13], v[10:11] op_sel:[1,0,0] op_sel_hi:[1,1,1]
	v_pk_fma_f32 v[8:9], v[188:189], s[14:15], v[8:9] op_sel:[1,0,0] op_sel_hi:[1,1,1]
	v_fmac_f32_e32 v22, s16, v189
	v_readlane_b32 s12, v0, 58
	v_readlane_b32 s13, v23, 58
	v_readlane_b32 s14, v24, 58
	v_readlane_b32 s15, v25, 58
	v_readlane_b32 s16, v26, 58
	s_waitcnt vmcnt(5)
	v_pk_fma_f32 v[10:11], v[190:191], s[12:13], v[10:11] op_sel_hi:[0,1,1]
	v_pk_fma_f32 v[8:9], v[190:191], s[14:15], v[8:9] op_sel_hi:[0,1,1]
	v_fmac_f32_e32 v22, s16, v190
	v_readlane_b32 s12, v0, 59
	v_readlane_b32 s13, v23, 59
	v_readlane_b32 s14, v24, 59
	v_readlane_b32 s15, v25, 59
	v_readlane_b32 s16, v26, 59
	s_waitcnt vmcnt(4)
	v_pk_fma_f32 v[10:11], v[190:191], s[12:13], v[10:11] op_sel:[1,0,0] op_sel_hi:[1,1,1]
	v_pk_fma_f32 v[8:9], v[190:191], s[14:15], v[8:9] op_sel:[1,0,0] op_sel_hi:[1,1,1]
	v_fmac_f32_e32 v22, s16, v191
	v_readlane_b32 s12, v0, 60
	v_readlane_b32 s13, v23, 60
	v_readlane_b32 s14, v24, 60
	v_readlane_b32 s15, v25, 60
	v_readlane_b32 s16, v26, 60
	s_waitcnt vmcnt(3)
	v_pk_fma_f32 v[10:11], v[192:193], s[12:13], v[10:11] op_sel_hi:[0,1,1]
	v_pk_fma_f32 v[8:9], v[192:193], s[14:15], v[8:9] op_sel_hi:[0,1,1]
	v_fmac_f32_e32 v22, s16, v192
	v_readlane_b32 s12, v0, 61
	v_readlane_b32 s13, v23, 61
	v_readlane_b32 s14, v24, 61
	v_readlane_b32 s15, v25, 61
	v_readlane_b32 s16, v26, 61
	s_waitcnt vmcnt(2)
	v_pk_fma_f32 v[10:11], v[192:193], s[12:13], v[10:11] op_sel:[1,0,0] op_sel_hi:[1,1,1]
	v_pk_fma_f32 v[8:9], v[192:193], s[14:15], v[8:9] op_sel:[1,0,0] op_sel_hi:[1,1,1]
	v_fmac_f32_e32 v22, s16, v193
	v_readlane_b32 s12, v0, 62
	v_readlane_b32 s13, v23, 62
	v_readlane_b32 s14, v24, 62
	v_readlane_b32 s15, v25, 62
	v_readlane_b32 s16, v26, 62
	s_waitcnt vmcnt(1)
	v_pk_fma_f32 v[10:11], v[194:195], s[12:13], v[10:11] op_sel_hi:[0,1,1]
	v_pk_fma_f32 v[8:9], v[194:195], s[14:15], v[8:9] op_sel_hi:[0,1,1]
	v_fmac_f32_e32 v22, s16, v194
	v_readlane_b32 s12, v0, 63
	v_readlane_b32 s13, v23, 63
	v_readlane_b32 s14, v24, 63
	v_readlane_b32 s15, v25, 63
	v_readlane_b32 s16, v26, 63
	s_waitcnt vmcnt(0)
	v_pk_fma_f32 v[10:11], v[194:195], s[12:13], v[10:11] op_sel:[1,0,0] op_sel_hi:[1,1,1]
	v_pk_fma_f32 v[8:9], v[194:195], s[14:15], v[8:9] op_sel:[1,0,0] op_sel_hi:[1,1,1]
	v_fmac_f32_e32 v22, s16, v195
	s_movk_i32 s12, 0x6000
	s_mov_b32 s13, 0x9000
	s_mov_b32 s14, 0xc000
	s_mov_b32 s15, 0xf000
	s_mov_b32 s16, 0x12000
	s_mov_b32 s70, 64
	s_mov_b64 s[8:9], 0
	s_and_b64 vcc, exec, s[6:7]
	s_cbranch_vccz .LBB0_20
	v_lshlrev_b32_e32 v0, 3, v17
	v_and_b32_e32 v6, 0xffffffc0, v0
	v_ashrrev_i32_e32 v7, 31, v6
	v_lshl_add_u64 v[6:7], v[6:7], 2, v[2:3]
	v_add_co_u32_e32 v12, vcc, 0x3000, v6
	global_store_dword v[6:7], v10, off
	s_nop 0
	v_addc_co_u32_e32 v13, vcc, 0, v7, vcc
	v_add_co_u32_e32 v10, vcc, 0x6000, v6
	global_store_dword v[12:13], v11, off
	s_nop 0
	v_addc_co_u32_e32 v11, vcc, 0, v7, vcc
	global_store_dword v[10:11], v8, off
	v_add_co_u32_e32 v10, vcc, 0x9000, v6
	v_add_u32_e32 v17, s33, v17
	s_nop 0
	v_addc_co_u32_e32 v11, vcc, 0, v7, vcc
	v_add_co_u32_e32 v6, vcc, 0xc000, v6
	v_add_u32_e32 v19, s3, v19
	s_nop 0
	v_addc_co_u32_e32 v7, vcc, 0, v7, vcc
	v_cmp_lt_i32_e32 vcc, s69, v17
	s_or_b64 s[4:5], vcc, s[4:5]
	global_store_dword v[10:11], v9, off
	global_store_dword v[6:7], v22, off
	s_andn2_b64 exec, exec, s[4:5]
	s_cbranch_execnz .LBB0_19
